# band copies: rescale in band bubble no longer leaves a pending correction (QKB is issued after it)
# baseline (speedup 1.0000x reference)
.Lfa_rareA_b1:
	s_nop 7
	v_mov_b32_e32 v15, v0
	s_nop 1
	v_permlane32_swap_b32_e32 v0, v15
	v_max_f32_e32 v0, v0, v15
	v_max_f32_e32 v0, v0, v0
	v_max_f32_e32 v0, 0, v0
	v_exp_f32_e64 v15, -v0
	v_sub_f32_e32 v96, v96, v0
	v_sub_f32_e32 v97, v97, v0
	v_sub_f32_e32 v98, v98, v0
	v_sub_f32_e32 v99, v99, v0
	v_sub_f32_e32 v100, v100, v0
	v_sub_f32_e32 v101, v101, v0
	v_sub_f32_e32 v102, v102, v0
	v_sub_f32_e32 v103, v103, v0
	v_sub_f32_e32 v104, v104, v0
	v_sub_f32_e32 v105, v105, v0
	v_sub_f32_e32 v106, v106, v0
	v_sub_f32_e32 v107, v107, v0
	v_sub_f32_e32 v108, v108, v0
	v_sub_f32_e32 v109, v109, v0
	v_sub_f32_e32 v110, v110, v0
	v_sub_f32_e32 v111, v111, v0
	v_sub_f32_e32 v112, v112, v0
	v_sub_f32_e32 v113, v113, v0
	v_sub_f32_e32 v114, v114, v0
	v_sub_f32_e32 v115, v115, v0
	v_sub_f32_e32 v116, v116, v0
	v_sub_f32_e32 v117, v117, v0
	v_sub_f32_e32 v118, v118, v0
	v_sub_f32_e32 v119, v119, v0
	v_sub_f32_e32 v120, v120, v0
	v_sub_f32_e32 v121, v121, v0
	v_sub_f32_e32 v122, v122, v0
	v_sub_f32_e32 v123, v123, v0
	v_sub_f32_e32 v124, v124, v0
	v_sub_f32_e32 v125, v125, v0
	v_sub_f32_e32 v126, v126, v0
	v_sub_f32_e32 v127, v127, v0
	v_sub_f32_e32 v80, v80, v0
	v_sub_f32_e32 v81, v81, v0
	v_sub_f32_e32 v82, v82, v0
	v_sub_f32_e32 v83, v83, v0
	v_sub_f32_e32 v84, v84, v0
	v_sub_f32_e32 v85, v85, v0
	v_sub_f32_e32 v86, v86, v0
	v_sub_f32_e32 v87, v87, v0
	v_sub_f32_e32 v88, v88, v0
	v_sub_f32_e32 v89, v89, v0
	v_sub_f32_e32 v90, v90, v0
	v_sub_f32_e32 v91, v91, v0
	v_sub_f32_e32 v92, v92, v0
	v_sub_f32_e32 v93, v93, v0
	v_sub_f32_e32 v94, v94, v0
	v_sub_f32_e32 v95, v95, v0
	v_mul_f32_e32 v16, v16, v15
	v_mul_f32_e32 v17, v17, v15
	v_mul_f32_e32 v18, v18, v15
	v_mul_f32_e32 v19, v19, v15
	v_mul_f32_e32 v20, v20, v15
	v_mul_f32_e32 v21, v21, v15
	v_mul_f32_e32 v22, v22, v15
	v_mul_f32_e32 v23, v23, v15
	v_mul_f32_e32 v24, v24, v15
	v_mul_f32_e32 v25, v25, v15
	v_mul_f32_e32 v26, v26, v15
	v_mul_f32_e32 v27, v27, v15
	v_mul_f32_e32 v28, v28, v15
	v_mul_f32_e32 v29, v29, v15
	v_mul_f32_e32 v30, v30, v15
	v_mul_f32_e32 v31, v31, v15
	v_mul_f32_e32 v32, v32, v15
	v_mul_f32_e32 v33, v33, v15
	v_mul_f32_e32 v34, v34, v15
	v_mul_f32_e32 v35, v35, v15
	v_mul_f32_e32 v36, v36, v15
	v_mul_f32_e32 v37, v37, v15
	v_mul_f32_e32 v38, v38, v15
	v_mul_f32_e32 v39, v39, v15
	v_mul_f32_e32 v40, v40, v15
	v_mul_f32_e32 v41, v41, v15
	v_mul_f32_e32 v42, v42, v15
	v_mul_f32_e32 v43, v43, v15
	v_mul_f32_e32 v44, v44, v15
	v_mul_f32_e32 v45, v45, v15
	v_mul_f32_e32 v46, v46, v15
	v_mul_f32_e32 v47, v47, v15
	v_mul_f32_e32 v48, v48, v15
	v_mul_f32_e32 v49, v49, v15
	v_mul_f32_e32 v50, v50, v15
	v_mul_f32_e32 v51, v51, v15
	v_mul_f32_e32 v52, v52, v15
	v_mul_f32_e32 v53, v53, v15
	v_mul_f32_e32 v54, v54, v15
	v_mul_f32_e32 v55, v55, v15
	v_mul_f32_e32 v56, v56, v15
	v_mul_f32_e32 v57, v57, v15
	v_mul_f32_e32 v58, v58, v15
	v_mul_f32_e32 v59, v59, v15
	v_mul_f32_e32 v60, v60, v15
	v_mul_f32_e32 v61, v61, v15
	v_mul_f32_e32 v62, v62, v15
	v_mul_f32_e32 v63, v63, v15
	v_mul_f32_e32 v64, v64, v15
	v_mul_f32_e32 v65, v65, v15
	v_mul_f32_e32 v66, v66, v15
	v_mul_f32_e32 v67, v67, v15
	v_mul_f32_e32 v68, v68, v15
	v_mul_f32_e32 v69, v69, v15
	v_mul_f32_e32 v70, v70, v15
	v_mul_f32_e32 v71, v71, v15
	v_mul_f32_e32 v72, v72, v15
	v_mul_f32_e32 v73, v73, v15
	v_mul_f32_e32 v74, v74, v15
	v_mul_f32_e32 v75, v75, v15
	v_mul_f32_e32 v76, v76, v15
	v_mul_f32_e32 v77, v77, v15
	v_mul_f32_e32 v78, v78, v15
	v_mul_f32_e32 v79, v79, v15
	v_mul_f32_e32 v159, v159, v15
	s_nop 1
	s_branch .Lfa_retA_b1
